# MLA loop: the lgkmcnt wait for the next MFMA's fragment sits right behind the ds_read, so each VALU run flows straight into its MFMA
# speedup vs baseline: 1.0534x; 1.0056x over previous
.LBB0_500:
	s_mul_hi_u32 s9, s48, 0xaaaaaaab
	s_lshr_b32 s9, s9, 2
	s_mul_i32 s9, s9, 0xfffe2000
	s_add_i32 s52, s9, 0
	v_add_u32_e32 v141, s50, v139
	v_add_u32_e32 v220, s52, v141
	v_mfma_f32_32x32x16_bf16 v[66:81], v[142:145], v[134:137], v[66:81]
	ds_read_b128 v[224:227], v140 offset:14336
	s_waitcnt lgkmcnt(4)
	v_exp_f32_e32 v26, v26
	v_exp_f32_e32 v27, v27
	v_exp_f32_e32 v28, v28
	v_mfma_f32_32x32x16_bf16 v[82:97], v[146:149], v[134:137], v[82:97]
	ds_read_b128 v[228:231], v140 offset:14848
	s_waitcnt lgkmcnt(4)
	v_exp_f32_e32 v29, v29
	v_exp_f32_e32 v30, v30
	v_exp_f32_e32 v31, v31
	v_mfma_f32_32x32x16_bf16 v[50:65], v[150:153], v[118:121], 0
	ds_read_b128 v[232:235], v140 offset:26624
	s_waitcnt lgkmcnt(4)
	v_exp_f32_e32 v32, v32
	v_exp_f32_e32 v33, v33
	v_add_f32_e32 v163, v163, v26
	v_add_f32_e32 v162, v162, v27
	v_mfma_f32_32x32x16_bf16 v[50:65], v[154:157], v[114:117], v[50:65]
	ds_read_b128 v[142:145], v140 offset:28672
	s_waitcnt lgkmcnt(4)
	v_add_f32_e32 v163, v163, v28
	v_add_f32_e32 v162, v162, v29
	v_add_f32_e32 v163, v163, v30
	v_cvt_pk_bf16_f32 v130, v26, v27
	v_cvt_pk_bf16_f32 v131, v28, v29
	v_mfma_f32_32x32x16_bf16 v[50:65], v[158:161], v[110:113], v[50:65]
	ds_read_b128 v[146:149], v140 offset:30720
	s_waitcnt lgkmcnt(4)
	v_cvt_pk_bf16_f32 v132, v30, v31
	v_cvt_pk_bf16_f32 v133, v32, v33
	v_add_f32_e32 v162, v162, v31
	v_add_f32_e32 v163, v163, v32
	v_add_f32_e32 v162, v162, v33
	v_mfma_f32_32x32x16_bf16 v[66:81], v[224:227], v[130:133], v[66:81]
	ds_read_b128 v[150:153], v140 offset:16384
	s_waitcnt lgkmcnt(4)
	v_exp_f32_e32 v2, v2
	v_exp_f32_e32 v3, v3
	v_exp_f32_e32 v4, v4
	v_mfma_f32_32x32x16_bf16 v[82:97], v[228:231], v[130:133], v[82:97]
	ds_read_b128 v[154:157], v140 offset:16896
	s_waitcnt lgkmcnt(4)
	v_exp_f32_e32 v5, v5
	v_exp_f32_e32 v6, v6
	v_exp_f32_e32 v7, v7
	v_mfma_f32_32x32x16_bf16 v[50:65], v[232:235], v[106:109], v[50:65]
	ds_read_b128 v[158:161], v140 offset:20992
	s_waitcnt lgkmcnt(4)
	v_exp_f32_e32 v8, v8
	v_exp_f32_e32 v9, v9
	v_add_f32_e32 v163, v163, v2
	v_add_f32_e32 v162, v162, v3
	v_mfma_f32_32x32x16_bf16 v[50:65], v[142:145], v[102:105], v[50:65]
	ds_read_b128 v[224:227], v140 offset:23040
	s_waitcnt lgkmcnt(4)
	v_add_f32_e32 v163, v163, v4
	v_add_f32_e32 v162, v162, v5
	v_add_f32_e32 v163, v163, v6
	v_cvt_pk_bf16_f32 v134, v2, v3
	v_cvt_pk_bf16_f32 v135, v4, v5
	v_mfma_f32_32x32x16_bf16 v[50:65], v[146:149], v[98:101], v[50:65]
	ds_read_b128 v[228:231], v140 offset:25088
	s_waitcnt lgkmcnt(4)
	v_cvt_pk_bf16_f32 v136, v6, v7
	v_cvt_pk_bf16_f32 v137, v8, v9
	v_add_f32_e32 v162, v162, v7
	v_add_f32_e32 v163, v163, v8
	v_add_f32_e32 v162, v162, v9
	v_mfma_f32_32x32x16_bf16 v[66:81], v[150:153], v[134:137], v[66:81]
	ds_read_b128 v[232:235], v140 offset:18432
	s_waitcnt lgkmcnt(4)
	v_exp_f32_e32 v10, v10
	v_exp_f32_e32 v11, v11
	v_exp_f32_e32 v12, v12
	v_mfma_f32_32x32x16_bf16 v[82:97], v[154:157], v[134:137], v[82:97]
	ds_read_b128 v[142:145], v140 offset:18944
	s_waitcnt lgkmcnt(4)
	v_exp_f32_e32 v13, v13
	v_exp_f32_e32 v14, v14
	v_exp_f32_e32 v15, v15
	v_mfma_f32_32x32x16_bf16 v[34:49], v[158:161], v[118:121], 0
	ds_read_b128 v[146:149], v140 offset:27136
	s_waitcnt lgkmcnt(4)
	v_exp_f32_e32 v16, v16
	v_exp_f32_e32 v17, v17
	v_add_f32_e32 v163, v163, v10
	v_add_f32_e32 v162, v162, v11
	v_mfma_f32_32x32x16_bf16 v[34:49], v[224:227], v[114:117], v[34:49]
	ds_read_b128 v[150:153], v140 offset:29184
	s_waitcnt lgkmcnt(4)
	v_add_f32_e32 v163, v163, v12
	v_add_f32_e32 v162, v162, v13
	v_add_f32_e32 v163, v163, v14
	v_cvt_pk_bf16_f32 v130, v10, v11
	v_cvt_pk_bf16_f32 v131, v12, v13
	v_mfma_f32_32x32x16_bf16 v[34:49], v[228:231], v[110:113], v[34:49]
	ds_read_b128 v[154:157], v140 offset:31232
	s_waitcnt lgkmcnt(4)
	v_cvt_pk_bf16_f32 v132, v14, v15
	v_cvt_pk_bf16_f32 v133, v16, v17
	v_add_f32_e32 v162, v162, v15
	v_add_f32_e32 v163, v163, v16
	v_add_f32_e32 v162, v162, v17
	v_mfma_f32_32x32x16_bf16 v[66:81], v[232:235], v[130:133], v[66:81]
	ds_read_b128 v[158:161], v140 offset:32768
	s_waitcnt lgkmcnt(4)
	v_exp_f32_e32 v50, v50
	v_exp_f32_e32 v51, v51
	v_exp_f32_e32 v52, v52
	v_mfma_f32_32x32x16_bf16 v[82:97], v[142:145], v[130:133], v[82:97]
	ds_read_b128 v[224:227], v140 offset:33280
	s_waitcnt lgkmcnt(4)
	v_exp_f32_e32 v53, v53
	v_exp_f32_e32 v54, v54
	v_exp_f32_e32 v55, v55
	v_mfma_f32_32x32x16_bf16 v[34:49], v[146:149], v[106:109], v[34:49]
	ds_read_b128 v[228:231], v220 offset:40960
	s_waitcnt lgkmcnt(4)
	v_exp_f32_e32 v56, v56
	v_exp_f32_e32 v57, v57
	v_add_f32_e32 v163, v163, v50
	v_add_f32_e32 v162, v162, v51
	v_mfma_f32_32x32x16_bf16 v[34:49], v[150:153], v[102:105], v[34:49]
	ds_read_b128 v[232:235], v220 offset:43008
	s_waitcnt lgkmcnt(4)
	v_add_f32_e32 v163, v163, v52
	v_add_f32_e32 v162, v162, v53
	v_add_f32_e32 v163, v163, v54
	v_cvt_pk_bf16_f32 v134, v50, v51
	v_cvt_pk_bf16_f32 v135, v52, v53
	v_mfma_f32_32x32x16_bf16 v[34:49], v[154:157], v[98:101], v[34:49]
	ds_read_b128 v[142:145], v220 offset:45056
	s_waitcnt lgkmcnt(4)
	v_cvt_pk_bf16_f32 v136, v54, v55
	v_cvt_pk_bf16_f32 v137, v56, v57
	v_add_f32_e32 v162, v162, v55
	v_add_f32_e32 v163, v163, v56
	v_add_f32_e32 v162, v162, v57
	s_add_i32 s10, s51, 4
	s_cmp_le_i32 s10, s27
	s_cbranch_scc0 .Lmla_i2_last
	v_mfma_f32_32x32x16_bf16 v[66:81], v[158:161], v[134:137], v[66:81]
	ds_read_b128 v[146:149], v140 offset:34816
	s_waitcnt lgkmcnt(4)
	v_exp_f32_e32 v58, v58
	v_exp_f32_e32 v59, v59
	v_exp_f32_e32 v60, v60
	v_mfma_f32_32x32x16_bf16 v[82:97], v[224:227], v[134:137], v[82:97]
	ds_read_b128 v[150:153], v140 offset:35328
	s_waitcnt lgkmcnt(4)
	v_exp_f32_e32 v61, v61
	v_exp_f32_e32 v62, v62
	v_exp_f32_e32 v63, v63
	v_mfma_f32_32x32x16_bf16 v[18:33], v[228:231], v[118:121], 0
	ds_read_b128 v[154:157], v220 offset:47104
	s_waitcnt lgkmcnt(4)
	v_exp_f32_e32 v64, v64
	v_exp_f32_e32 v65, v65
	v_add_f32_e32 v163, v163, v58
	v_add_f32_e32 v162, v162, v59
	v_mfma_f32_32x32x16_bf16 v[18:33], v[232:235], v[114:117], v[18:33]
	ds_read_b128 v[158:161], v220 offset:49152
	s_waitcnt lgkmcnt(4)
	v_add_f32_e32 v163, v163, v60
	v_add_f32_e32 v162, v162, v61
	v_add_f32_e32 v163, v163, v62
	v_cvt_pk_bf16_f32 v130, v58, v59
	v_cvt_pk_bf16_f32 v131, v60, v61
	v_mfma_f32_32x32x16_bf16 v[18:33], v[142:145], v[110:113], v[18:33]
	ds_read_b128 v[224:227], v220 offset:51200
	s_waitcnt lgkmcnt(4)
	v_cvt_pk_bf16_f32 v132, v62, v63
	v_cvt_pk_bf16_f32 v133, v64, v65
	v_add_f32_e32 v162, v162, v63
	v_add_f32_e32 v163, v163, v64
	v_add_f32_e32 v162, v162, v65
	v_mfma_f32_32x32x16_bf16 v[66:81], v[146:149], v[130:133], v[66:81]
	ds_read_b128 v[228:231], v140 offset:36864
	s_waitcnt lgkmcnt(4)
	v_exp_f32_e32 v34, v34
	v_exp_f32_e32 v35, v35
	v_exp_f32_e32 v36, v36
	v_mfma_f32_32x32x16_bf16 v[82:97], v[150:153], v[130:133], v[82:97]
	ds_read_b128 v[232:235], v140 offset:37376
	s_waitcnt lgkmcnt(4)
	v_exp_f32_e32 v37, v37
	v_exp_f32_e32 v38, v38
	v_exp_f32_e32 v39, v39
	v_mfma_f32_32x32x16_bf16 v[18:33], v[154:157], v[106:109], v[18:33]
	ds_read_b128 v[142:145], v220 offset:41472
	s_waitcnt lgkmcnt(4)
	v_exp_f32_e32 v40, v40
	v_exp_f32_e32 v41, v41
	v_add_f32_e32 v163, v163, v34
	v_add_f32_e32 v162, v162, v35
	v_mfma_f32_32x32x16_bf16 v[18:33], v[158:161], v[102:105], v[18:33]
	ds_read_b128 v[146:149], v220 offset:43520
	s_waitcnt lgkmcnt(4)
	v_add_f32_e32 v163, v163, v36
	v_add_f32_e32 v162, v162, v37
	v_add_f32_e32 v163, v163, v38
	v_cvt_pk_bf16_f32 v134, v34, v35
	v_cvt_pk_bf16_f32 v135, v36, v37
	v_mfma_f32_32x32x16_bf16 v[18:33], v[224:227], v[98:101], v[18:33]
	ds_read_b128 v[150:153], v220 offset:45568
	s_waitcnt lgkmcnt(4)
	v_cvt_pk_bf16_f32 v136, v38, v39
	v_cvt_pk_bf16_f32 v137, v40, v41
	v_add_f32_e32 v162, v162, v39
	v_add_f32_e32 v163, v163, v40
	v_add_f32_e32 v162, v162, v41
	v_mfma_f32_32x32x16_bf16 v[66:81], v[228:231], v[134:137], v[66:81]
	ds_read_b128 v[154:157], v140 offset:38912
	s_waitcnt lgkmcnt(4)
	v_exp_f32_e32 v42, v42
	v_exp_f32_e32 v43, v43
	v_exp_f32_e32 v44, v44
	v_mfma_f32_32x32x16_bf16 v[82:97], v[232:235], v[134:137], v[82:97]
	ds_read_b128 v[158:161], v140 offset:39424
	s_waitcnt lgkmcnt(4)
	v_exp_f32_e32 v45, v45
	v_exp_f32_e32 v46, v46
	v_exp_f32_e32 v47, v47
	v_mfma_f32_32x32x16_bf16 v[2:17], v[142:145], v[118:121], 0
	ds_read_b128 v[224:227], v220 offset:47616
	s_waitcnt lgkmcnt(4)
	v_exp_f32_e32 v48, v48
	v_exp_f32_e32 v49, v49
	v_add_f32_e32 v163, v163, v42
	v_add_f32_e32 v162, v162, v43
	v_mfma_f32_32x32x16_bf16 v[2:17], v[146:149], v[114:117], v[2:17]
	ds_read_b128 v[228:231], v220 offset:49664
	s_waitcnt lgkmcnt(4)
	v_add_f32_e32 v163, v163, v44
	v_add_f32_e32 v162, v162, v45
	v_add_f32_e32 v163, v163, v46
	v_cvt_pk_bf16_f32 v130, v42, v43
	v_cvt_pk_bf16_f32 v131, v44, v45
	v_mfma_f32_32x32x16_bf16 v[2:17], v[150:153], v[110:113], v[2:17]
	ds_read_b128 v[232:235], v220 offset:51712
	s_waitcnt lgkmcnt(4)
	v_cvt_pk_bf16_f32 v132, v46, v47
	v_cvt_pk_bf16_f32 v133, v48, v49
	v_add_f32_e32 v162, v162, v47
	v_add_f32_e32 v163, v163, v48
	v_add_f32_e32 v162, v162, v49
	v_mfma_f32_32x32x16_bf16 v[66:81], v[154:157], v[130:133], v[66:81]
	v_add_u32_e32 v140, 0xa000, v220
	ds_read_b128 v[142:145], v140 offset:12288
	s_waitcnt lgkmcnt(4)
	v_exp_f32_e32 v18, v18
	v_exp_f32_e32 v19, v19
	v_exp_f32_e32 v20, v20
	v_mfma_f32_32x32x16_bf16 v[82:97], v[158:161], v[130:133], v[82:97]
	ds_read_b128 v[146:149], v140 offset:12800
	s_waitcnt lgkmcnt(4)
	v_exp_f32_e32 v21, v21
	v_exp_f32_e32 v22, v22
	v_exp_f32_e32 v23, v23
	v_mfma_f32_32x32x16_bf16 v[2:17], v[224:227], v[106:109], v[2:17]
	ds_read_b128 v[150:153], v140 offset:20480
	s_waitcnt lgkmcnt(4)
	v_exp_f32_e32 v24, v24
	v_exp_f32_e32 v25, v25
	v_add_f32_e32 v163, v163, v18
	v_add_f32_e32 v162, v162, v19
	v_mfma_f32_32x32x16_bf16 v[2:17], v[228:231], v[102:105], v[2:17]
	ds_read_b128 v[154:157], v140 offset:22528
	s_waitcnt lgkmcnt(4)
	v_add_f32_e32 v163, v163, v20
	v_add_f32_e32 v162, v162, v21
	v_add_f32_e32 v163, v163, v22
	v_cvt_pk_bf16_f32 v134, v18, v19
	v_cvt_pk_bf16_f32 v135, v20, v21
	v_mfma_f32_32x32x16_bf16 v[2:17], v[232:235], v[98:101], v[2:17]
	ds_read_b128 v[158:161], v140 offset:24576
	s_waitcnt lgkmcnt(4)
	v_cvt_pk_bf16_f32 v136, v22, v23
	v_cvt_pk_bf16_f32 v137, v24, v25
	v_add_f32_e32 v162, v162, v23
	v_add_f32_e32 v163, v163, v24
	v_add_f32_e32 v162, v162, v25
	s_add_i32 s48, s48, 2
	s_add_i32 s9, s51, 2
	s_add_u32 s29, s29, 0x4000
	s_addc_u32 s30, s30, 0
	s_add_u32 s31, s31, 0x6000
	s_addc_u32 s33, s33, 0
	s_add_i32 s49, s49, 2
	s_add_i32 s50, s50, 0xa000
	s_mov_b32 s51, s9
	s_branch .LBB0_496
.Lmla_i2_last:
	v_mfma_f32_32x32x16_bf16 v[66:81], v[158:161], v[134:137], v[66:81]
	ds_read_b128 v[146:149], v140 offset:34816
	s_waitcnt lgkmcnt(4)
	v_exp_f32_e32 v58, v58
	v_exp_f32_e32 v59, v59
	v_exp_f32_e32 v60, v60
	v_mfma_f32_32x32x16_bf16 v[82:97], v[224:227], v[134:137], v[82:97]
	ds_read_b128 v[150:153], v140 offset:35328
	s_waitcnt lgkmcnt(4)
	v_exp_f32_e32 v61, v61
	v_exp_f32_e32 v62, v62
	v_exp_f32_e32 v63, v63
	v_mfma_f32_32x32x16_bf16 v[18:33], v[228:231], v[118:121], 0
	ds_read_b128 v[154:157], v220 offset:47104
	s_waitcnt lgkmcnt(4)
	v_exp_f32_e32 v64, v64
	v_exp_f32_e32 v65, v65
	v_add_f32_e32 v163, v163, v58
	v_add_f32_e32 v162, v162, v59
	v_mfma_f32_32x32x16_bf16 v[18:33], v[232:235], v[114:117], v[18:33]
	ds_read_b128 v[158:161], v220 offset:49152
	s_waitcnt lgkmcnt(4)
	v_add_f32_e32 v163, v163, v60
	v_add_f32_e32 v162, v162, v61
	v_add_f32_e32 v163, v163, v62
	v_cvt_pk_bf16_f32 v130, v58, v59
	v_cvt_pk_bf16_f32 v131, v60, v61
	v_mfma_f32_32x32x16_bf16 v[18:33], v[142:145], v[110:113], v[18:33]
	ds_read_b128 v[224:227], v220 offset:51200
	s_waitcnt lgkmcnt(4)
	v_cvt_pk_bf16_f32 v132, v62, v63
	v_cvt_pk_bf16_f32 v133, v64, v65
	v_add_f32_e32 v162, v162, v63
	v_add_f32_e32 v163, v163, v64
	v_add_f32_e32 v162, v162, v65
	v_mfma_f32_32x32x16_bf16 v[66:81], v[146:149], v[130:133], v[66:81]
	ds_read_b128 v[228:231], v140 offset:36864
	s_waitcnt lgkmcnt(4)
	v_exp_f32_e32 v34, v34
	v_exp_f32_e32 v35, v35
	v_exp_f32_e32 v36, v36
	v_mfma_f32_32x32x16_bf16 v[82:97], v[150:153], v[130:133], v[82:97]
	ds_read_b128 v[232:235], v140 offset:37376
	s_waitcnt lgkmcnt(4)
	v_exp_f32_e32 v37, v37
	v_exp_f32_e32 v38, v38
	v_exp_f32_e32 v39, v39
	v_mfma_f32_32x32x16_bf16 v[18:33], v[154:157], v[106:109], v[18:33]
	ds_read_b128 v[142:145], v220 offset:41472
	s_waitcnt lgkmcnt(4)
	v_exp_f32_e32 v40, v40
	v_exp_f32_e32 v41, v41
	v_add_f32_e32 v163, v163, v34
	v_add_f32_e32 v162, v162, v35
	v_mfma_f32_32x32x16_bf16 v[18:33], v[158:161], v[102:105], v[18:33]
	ds_read_b128 v[146:149], v220 offset:43520
	s_waitcnt lgkmcnt(4)
	v_add_f32_e32 v163, v163, v36
	v_add_f32_e32 v162, v162, v37
	v_add_f32_e32 v163, v163, v38
	v_cvt_pk_bf16_f32 v134, v34, v35
	v_cvt_pk_bf16_f32 v135, v36, v37
	v_mfma_f32_32x32x16_bf16 v[18:33], v[224:227], v[98:101], v[18:33]
	ds_read_b128 v[150:153], v220 offset:45568
	s_waitcnt lgkmcnt(4)
	v_cvt_pk_bf16_f32 v136, v38, v39
	v_cvt_pk_bf16_f32 v137, v40, v41
	v_add_f32_e32 v162, v162, v39
	v_add_f32_e32 v163, v163, v40
	v_add_f32_e32 v162, v162, v41
	v_mfma_f32_32x32x16_bf16 v[66:81], v[228:231], v[134:137], v[66:81]
	ds_read_b128 v[154:157], v140 offset:38912
	s_waitcnt lgkmcnt(4)
	v_exp_f32_e32 v42, v42
	v_exp_f32_e32 v43, v43
	v_exp_f32_e32 v44, v44
	v_mfma_f32_32x32x16_bf16 v[82:97], v[232:235], v[134:137], v[82:97]
	ds_read_b128 v[158:161], v140 offset:39424
	s_waitcnt lgkmcnt(4)
	v_exp_f32_e32 v45, v45
	v_exp_f32_e32 v46, v46
	v_exp_f32_e32 v47, v47
	v_mfma_f32_32x32x16_bf16 v[2:17], v[142:145], v[118:121], 0
	ds_read_b128 v[224:227], v220 offset:47616
	s_waitcnt lgkmcnt(4)
	v_exp_f32_e32 v48, v48
	v_exp_f32_e32 v49, v49
	v_add_f32_e32 v163, v163, v42
	v_add_f32_e32 v162, v162, v43
	v_mfma_f32_32x32x16_bf16 v[2:17], v[146:149], v[114:117], v[2:17]
	ds_read_b128 v[228:231], v220 offset:49664
	s_waitcnt lgkmcnt(4)
	v_add_f32_e32 v163, v163, v44
	v_add_f32_e32 v162, v162, v45
	v_add_f32_e32 v163, v163, v46
	v_cvt_pk_bf16_f32 v130, v42, v43
	v_cvt_pk_bf16_f32 v131, v44, v45
	v_mfma_f32_32x32x16_bf16 v[2:17], v[150:153], v[110:113], v[2:17]
	ds_read_b128 v[232:235], v220 offset:51712
	s_waitcnt lgkmcnt(4)
	v_cvt_pk_bf16_f32 v132, v46, v47
	v_cvt_pk_bf16_f32 v133, v48, v49
	v_add_f32_e32 v162, v162, v47
	v_add_f32_e32 v163, v163, v48
	v_add_f32_e32 v162, v162, v49
	v_mfma_f32_32x32x16_bf16 v[66:81], v[154:157], v[130:133], v[66:81]
	s_waitcnt lgkmcnt(3)
	v_mfma_f32_32x32x16_bf16 v[82:97], v[158:161], v[130:133], v[82:97]
	s_waitcnt lgkmcnt(2)
	v_mfma_f32_32x32x16_bf16 v[2:17], v[224:227], v[106:109], v[2:17]
	s_waitcnt lgkmcnt(1)
	v_mfma_f32_32x32x16_bf16 v[2:17], v[228:231], v[102:105], v[2:17]
	s_waitcnt lgkmcnt(0)
	v_mfma_f32_32x32x16_bf16 v[2:17], v[232:235], v[98:101], v[2:17]
	v_add_f32_e32 v138, v138, v163
	s_nop 0
	v_add_f32_e32 v138, v138, v162
	s_add_i32 s48, s48, 2
	s_add_i32 s9, s51, 2
	s_add_u32 s29, s29, 0x4000
	s_addc_u32 s30, s30, 0
	s_add_u32 s31, s31, 0x6000
	s_addc_u32 s33, s33, 0
	s_add_i32 s49, s49, 2
	s_add_i32 s50, s50, 0xa000
	s_branch .LBB0_503
